# attention top-k: bit-plane radix select (transpose 64 f16 scores per lane into 16 bit planes; 16 passes of AND+popcount+DPP wave sum) replaces 32-pass compare/count loop
# speedup vs baseline: 1.0242x; 1.0242x over previous
; __device__ __forceinline__ void attn_phase(const int TID, const int BID, PP p, LAS unsigned char* lds) {
;     ...
;             const int nib = (Nk + 255) >> 8;
;             unsigned Tt = 0u;
;     ...
;                 const unsigned cand = Tt | (1u << bit);
;                 int c = 0;
; #pragma unroll
;                 for (int ib = 0; ib < 16; ++ib)
;                     if (ib < nib) {
; #pragma unroll
;                         for (int e = 0; e < 4; ++e) c += (key[4 * ib + e] >= cand) ? 1 : 0;
;                     }
;                 int cnt = 0;
; #pragma unroll
;                 for (int bp = 0; bp < 7; ++bp) cnt += __popcll(__ballot((c >> bp) & 1)) << bp;
;                 if (cnt >= 256) { Tt = cand; if (cnt == 256) break; }
;             }
.LBB0_136:
	s_or_b64 exec, exec, s[12:13]
	s_cmpk_gt_u32 s87, 0x1c0
	s_cselect_b64 s[40:41], -1, 0
	s_cmpk_gt_u32 s87, 0x2c0
	s_cselect_b64 s[42:43], -1, 0
	s_cmpk_gt_u32 s87, 0x3c0
	s_cselect_b64 s[44:45], -1, 0
	s_cmpk_gt_u32 s87, 0x4c0
	s_cselect_b64 s[46:47], -1, 0
	s_cmpk_gt_u32 s87, 0x5c0
	s_cselect_b64 s[48:49], -1, 0
	s_cmpk_gt_u32 s87, 0x6c0
	s_cselect_b64 s[50:51], -1, 0
	s_cmpk_gt_u32 s87, 0x7c0
	s_cselect_b64 s[52:53], -1, 0
	s_cmpk_gt_u32 s87, 0x8c0
	s_cselect_b64 s[54:55], -1, 0
	s_cmpk_gt_u32 s87, 0x9c0
	s_cselect_b64 s[56:57], -1, 0
	s_cmpk_gt_u32 s87, 0xac0
	s_cselect_b64 s[58:59], -1, 0
	s_cmpk_gt_u32 s87, 0xbc0
	s_cselect_b64 s[60:61], -1, 0
	s_cmpk_gt_u32 s87, 0xcc0
	s_cselect_b64 s[62:63], -1, 0
	s_cmpk_gt_u32 s87, 0xdc0
	s_cselect_b64 s[88:89], -1, 0
	s_cmpk_gt_u32 s87, 0xec0
	s_cselect_b64 s[80:81], -1, 0
	v_mov_b32_e32 v181, 0x0f0f0f0f
	v_mov_b32_e32 v182, 0x33333333
	v_mov_b32_e32 v183, 0x55555555
	v_mov_b32_e32 v184, 0x06020400
	v_mov_b32_e32 v185, 0x07030501
	v_perm_b32 v240, v216, v208, v184
	v_perm_b32 v248, v216, v208, v185
	v_perm_b32 v241, v217, v209, v184
	v_perm_b32 v249, v217, v209, v185
	v_perm_b32 v242, v218, v210, v184
	v_perm_b32 v250, v218, v210, v185
	v_perm_b32 v243, v219, v211, v184
	v_perm_b32 v251, v219, v211, v185
	v_perm_b32 v244, v220, v212, v184
	v_perm_b32 v252, v220, v212, v185
	v_perm_b32 v245, v221, v213, v184
	v_perm_b32 v253, v221, v213, v185
	v_perm_b32 v246, v222, v214, v184
	v_perm_b32 v196, v222, v214, v185
	v_perm_b32 v247, v223, v215, v184
	v_perm_b32 v197, v223, v215, v185
	v_lshlrev_b32_e32 v198, 4, v244
	v_bfi_b32 v208, v181, v240, v198
	v_lshrrev_b32_e32 v199, 4, v240
	v_bfi_b32 v212, v181, v199, v244
	v_lshlrev_b32_e32 v198, 4, v245
	v_bfi_b32 v209, v181, v241, v198
	v_lshrrev_b32_e32 v199, 4, v241
	v_bfi_b32 v213, v181, v199, v245
	v_lshlrev_b32_e32 v198, 4, v246
	v_bfi_b32 v210, v181, v242, v198
	v_lshrrev_b32_e32 v199, 4, v242
	v_bfi_b32 v214, v181, v199, v246
	v_lshlrev_b32_e32 v198, 4, v247
	v_bfi_b32 v211, v181, v243, v198
	v_lshrrev_b32_e32 v199, 4, v243
	v_bfi_b32 v215, v181, v199, v247
	v_lshlrev_b32_e32 v198, 4, v252
	v_bfi_b32 v216, v181, v248, v198
	v_lshrrev_b32_e32 v199, 4, v248
	v_bfi_b32 v220, v181, v199, v252
	v_lshlrev_b32_e32 v198, 4, v253
	v_bfi_b32 v217, v181, v249, v198
	v_lshrrev_b32_e32 v199, 4, v249
	v_bfi_b32 v221, v181, v199, v253
	v_lshlrev_b32_e32 v198, 4, v196
	v_bfi_b32 v218, v181, v250, v198
	v_lshrrev_b32_e32 v199, 4, v250
	v_bfi_b32 v222, v181, v199, v196
	v_lshlrev_b32_e32 v198, 4, v197
	v_bfi_b32 v219, v181, v251, v198
	v_lshrrev_b32_e32 v199, 4, v251
	v_bfi_b32 v223, v181, v199, v197
	v_lshlrev_b32_e32 v198, 2, v210
	v_bfi_b32 v240, v182, v208, v198
	v_lshrrev_b32_e32 v199, 2, v208
	v_bfi_b32 v242, v182, v199, v210
	v_lshlrev_b32_e32 v198, 2, v211
	v_bfi_b32 v241, v182, v209, v198
	v_lshrrev_b32_e32 v199, 2, v209
	v_bfi_b32 v243, v182, v199, v211
	v_lshlrev_b32_e32 v198, 2, v214
	v_bfi_b32 v244, v182, v212, v198
	v_lshrrev_b32_e32 v199, 2, v212
	v_bfi_b32 v246, v182, v199, v214
	v_lshlrev_b32_e32 v198, 2, v215
	v_bfi_b32 v245, v182, v213, v198
	v_lshrrev_b32_e32 v199, 2, v213
	v_bfi_b32 v247, v182, v199, v215
	v_lshlrev_b32_e32 v198, 2, v218
	v_bfi_b32 v248, v182, v216, v198
	v_lshrrev_b32_e32 v199, 2, v216
	v_bfi_b32 v250, v182, v199, v218
	v_lshlrev_b32_e32 v198, 2, v219
	v_bfi_b32 v249, v182, v217, v198
	v_lshrrev_b32_e32 v199, 2, v217
	v_bfi_b32 v251, v182, v199, v219
	v_lshlrev_b32_e32 v198, 2, v222
	v_bfi_b32 v252, v182, v220, v198
	v_lshrrev_b32_e32 v199, 2, v220
	v_bfi_b32 v196, v182, v199, v222
	v_lshlrev_b32_e32 v198, 2, v223
	v_bfi_b32 v253, v182, v221, v198
	v_lshrrev_b32_e32 v199, 2, v221
	v_bfi_b32 v197, v182, v199, v223
	v_lshlrev_b32_e32 v198, 1, v241
	v_bfi_b32 v208, v183, v240, v198
	v_lshrrev_b32_e32 v199, 1, v240
	v_bfi_b32 v209, v183, v199, v241
	v_lshlrev_b32_e32 v198, 1, v243
	v_bfi_b32 v210, v183, v242, v198
	v_lshrrev_b32_e32 v199, 1, v242
	v_bfi_b32 v211, v183, v199, v243
	v_lshlrev_b32_e32 v198, 1, v245
	v_bfi_b32 v212, v183, v244, v198
	v_lshrrev_b32_e32 v199, 1, v244
	v_bfi_b32 v213, v183, v199, v245
	v_lshlrev_b32_e32 v198, 1, v247
	v_bfi_b32 v214, v183, v246, v198
	v_lshrrev_b32_e32 v199, 1, v246
	v_bfi_b32 v215, v183, v199, v247
	v_lshlrev_b32_e32 v198, 1, v249
	v_bfi_b32 v216, v183, v248, v198
	v_lshrrev_b32_e32 v199, 1, v248
	v_bfi_b32 v217, v183, v199, v249
	v_lshlrev_b32_e32 v198, 1, v251
	v_bfi_b32 v218, v183, v250, v198
	v_lshrrev_b32_e32 v199, 1, v250
	v_bfi_b32 v219, v183, v199, v251
	v_lshlrev_b32_e32 v198, 1, v253
	v_bfi_b32 v220, v183, v252, v198
	v_lshrrev_b32_e32 v199, 1, v252
	v_bfi_b32 v221, v183, v199, v253
	v_lshlrev_b32_e32 v198, 1, v197
	v_bfi_b32 v222, v183, v196, v198
	v_lshrrev_b32_e32 v199, 1, v196
	v_bfi_b32 v223, v183, v199, v197
	v_perm_b32 v240, v232, v224, v184
	v_perm_b32 v248, v232, v224, v185
	v_perm_b32 v241, v233, v225, v184
	v_perm_b32 v249, v233, v225, v185
	v_perm_b32 v242, v234, v226, v184
	v_perm_b32 v250, v234, v226, v185
	v_perm_b32 v243, v235, v227, v184
	v_perm_b32 v251, v235, v227, v185
	v_perm_b32 v244, v236, v228, v184
	v_perm_b32 v252, v236, v228, v185
	v_perm_b32 v245, v237, v229, v184
	v_perm_b32 v253, v237, v229, v185
	v_perm_b32 v246, v238, v230, v184
	v_perm_b32 v196, v238, v230, v185
	v_perm_b32 v247, v239, v231, v184
	v_perm_b32 v197, v239, v231, v185
	v_lshlrev_b32_e32 v198, 4, v244
	v_bfi_b32 v224, v181, v240, v198
	v_lshrrev_b32_e32 v199, 4, v240
	v_bfi_b32 v228, v181, v199, v244
	v_lshlrev_b32_e32 v198, 4, v245
	v_bfi_b32 v225, v181, v241, v198
	v_lshrrev_b32_e32 v199, 4, v241
	v_bfi_b32 v229, v181, v199, v245
	v_lshlrev_b32_e32 v198, 4, v246
; __device__ __forceinline__ void attn_phase(const int TID, const int BID, PP p, LAS unsigned char* lds) {
;     ...
;                 const unsigned cand = Tt | (1u << bit);
;                 int c = 0;
; #pragma unroll
;                 for (int ib = 0; ib < 16; ++ib)
;                     if (ib < nib) {
; #pragma unroll
;                         for (int e = 0; e < 4; ++e) c += (key[4 * ib + e] >= cand) ? 1 : 0;
;                     }
;                 int cnt = 0;
; #pragma unroll
;                 for (int bp = 0; bp < 7; ++bp) cnt += __popcll(__ballot((c >> bp) & 1)) << bp;
;                 if (cnt >= 256) { Tt = cand; if (cnt == 256) break; }
;             }
	v_bfi_b32 v226, v181, v242, v198
	v_lshrrev_b32_e32 v199, 4, v242
	v_bfi_b32 v230, v181, v199, v246
	v_lshlrev_b32_e32 v198, 4, v247
	v_bfi_b32 v227, v181, v243, v198
	v_lshrrev_b32_e32 v199, 4, v243
	v_bfi_b32 v231, v181, v199, v247
	v_lshlrev_b32_e32 v198, 4, v252
	v_bfi_b32 v232, v181, v248, v198
	v_lshrrev_b32_e32 v199, 4, v248
	v_bfi_b32 v236, v181, v199, v252
	v_lshlrev_b32_e32 v198, 4, v253
	v_bfi_b32 v233, v181, v249, v198
	v_lshrrev_b32_e32 v199, 4, v249
	v_bfi_b32 v237, v181, v199, v253
	v_lshlrev_b32_e32 v198, 4, v196
	v_bfi_b32 v234, v181, v250, v198
	v_lshrrev_b32_e32 v199, 4, v250
	v_bfi_b32 v238, v181, v199, v196
	v_lshlrev_b32_e32 v198, 4, v197
	v_bfi_b32 v235, v181, v251, v198
	v_lshrrev_b32_e32 v199, 4, v251
	v_bfi_b32 v239, v181, v199, v197
	v_lshlrev_b32_e32 v198, 2, v226
	v_bfi_b32 v240, v182, v224, v198
	v_lshrrev_b32_e32 v199, 2, v224
	v_bfi_b32 v242, v182, v199, v226
	v_lshlrev_b32_e32 v198, 2, v227
	v_bfi_b32 v241, v182, v225, v198
	v_lshrrev_b32_e32 v199, 2, v225
	v_bfi_b32 v243, v182, v199, v227
	v_lshlrev_b32_e32 v198, 2, v230
	v_bfi_b32 v244, v182, v228, v198
	v_lshrrev_b32_e32 v199, 2, v228
	v_bfi_b32 v246, v182, v199, v230
	v_lshlrev_b32_e32 v198, 2, v231
	v_bfi_b32 v245, v182, v229, v198
	v_lshrrev_b32_e32 v199, 2, v229
	v_bfi_b32 v247, v182, v199, v231
	v_lshlrev_b32_e32 v198, 2, v234
	v_bfi_b32 v248, v182, v232, v198
	v_lshrrev_b32_e32 v199, 2, v232
	v_bfi_b32 v250, v182, v199, v234
	v_lshlrev_b32_e32 v198, 2, v235
	v_bfi_b32 v249, v182, v233, v198
	v_lshrrev_b32_e32 v199, 2, v233
	v_bfi_b32 v251, v182, v199, v235
	v_lshlrev_b32_e32 v198, 2, v238
	v_bfi_b32 v252, v182, v236, v198
	v_lshrrev_b32_e32 v199, 2, v236
	v_bfi_b32 v196, v182, v199, v238
	v_lshlrev_b32_e32 v198, 2, v239
	v_bfi_b32 v253, v182, v237, v198
	v_lshrrev_b32_e32 v199, 2, v237
	v_bfi_b32 v197, v182, v199, v239
	v_lshlrev_b32_e32 v198, 1, v241
	v_bfi_b32 v224, v183, v240, v198
	v_lshrrev_b32_e32 v199, 1, v240
	v_bfi_b32 v225, v183, v199, v241
	v_lshlrev_b32_e32 v198, 1, v243
	v_bfi_b32 v226, v183, v242, v198
	v_lshrrev_b32_e32 v199, 1, v242
	v_bfi_b32 v227, v183, v199, v243
	v_lshlrev_b32_e32 v198, 1, v245
	v_bfi_b32 v228, v183, v244, v198
	v_lshrrev_b32_e32 v199, 1, v244
	v_bfi_b32 v229, v183, v199, v245
	v_lshlrev_b32_e32 v198, 1, v247
	v_bfi_b32 v230, v183, v246, v198
	v_lshrrev_b32_e32 v199, 1, v246
	v_bfi_b32 v231, v183, v199, v247
	v_lshlrev_b32_e32 v198, 1, v249
	v_bfi_b32 v232, v183, v248, v198
	v_lshrrev_b32_e32 v199, 1, v248
	v_bfi_b32 v233, v183, v199, v249
	v_lshlrev_b32_e32 v198, 1, v251
	v_bfi_b32 v234, v183, v250, v198
	v_lshrrev_b32_e32 v199, 1, v250
	v_bfi_b32 v235, v183, v199, v251
	v_lshlrev_b32_e32 v198, 1, v253
	v_bfi_b32 v236, v183, v252, v198
	v_lshrrev_b32_e32 v199, 1, v252
	v_bfi_b32 v237, v183, v199, v253
	v_lshlrev_b32_e32 v198, 1, v197
	v_bfi_b32 v238, v183, v196, v198
	v_lshrrev_b32_e32 v199, 1, v196
	v_bfi_b32 v239, v183, v199, v197
	v_xor_b32_e32 v208, v208, v223
	v_xor_b32_e32 v209, v209, v223
	v_xor_b32_e32 v210, v210, v223
	v_xor_b32_e32 v211, v211, v223
	v_xor_b32_e32 v212, v212, v223
	v_xor_b32_e32 v213, v213, v223
	v_xor_b32_e32 v214, v214, v223
	v_xor_b32_e32 v215, v215, v223
	v_xor_b32_e32 v216, v216, v223
	v_xor_b32_e32 v217, v217, v223
	v_xor_b32_e32 v218, v218, v223
	v_xor_b32_e32 v219, v219, v223
	v_xor_b32_e32 v220, v220, v223
	v_xor_b32_e32 v221, v221, v223
	v_xor_b32_e32 v222, v222, v223
	v_not_b32_e32 v223, v223
	v_xor_b32_e32 v224, v224, v239
	v_xor_b32_e32 v225, v225, v239
	v_xor_b32_e32 v226, v226, v239
	v_xor_b32_e32 v227, v227, v239
	v_xor_b32_e32 v228, v228, v239
	v_xor_b32_e32 v229, v229, v239
	v_xor_b32_e32 v230, v230, v239
	v_xor_b32_e32 v231, v231, v239
	v_xor_b32_e32 v232, v232, v239
	v_xor_b32_e32 v233, v233, v239
	v_xor_b32_e32 v234, v234, v239
	v_xor_b32_e32 v235, v235, v239
	v_xor_b32_e32 v236, v236, v239
	v_xor_b32_e32 v237, v237, v239
	v_xor_b32_e32 v238, v238, v239
	v_not_b32_e32 v239, v239
	s_lshr_b32 s10, s72, 8
	s_bfe_u32 s11, s72, 0x60002
	s_min_u32 s12, s10, 8
	s_lshl_b32 s12, s12, 1
	s_lshl_b32 s13, 1, s12
	s_sub_u32 s13, s13, 1
	s_mul_i32 s13, s13, 0x10001
	s_sub_i32 s14, s10, 8
	s_max_i32 s14, s14, 0
	s_lshl_b32 s14, s14, 1
	s_lshl_b32 s15, 1, s14
	s_sub_u32 s15, s15, 1
	s_mul_i32 s15, s15, 0x10001
	s_and_b32 s16, s10, 7
	s_lshl_b32 s16, s16, 1
	s_lshl_b32 s17, 0x30003, s16
	s_cmp_lt_u32 s10, 8
	s_cselect_b32 s18, s17, 0
	s_cselect_b32 s19, 0, s17
	v_cmp_gt_u32_e32 vcc, s11, v83
	v_mov_b32_e32 v198, s18
	v_mov_b32_e32 v199, s19
	v_mov_b32_e32 v200, s13
	v_mov_b32_e32 v201, s15
	v_cndmask_b32_e32 v198, 0, v198, vcc
	v_cndmask_b32_e32 v199, 0, v199, vcc
	v_or_b32_e32 v200, v200, v198
	v_or_b32_e32 v201, v201, v199
	s_movk_i32 s20, 0x100
	s_mov_b32 s21, 0
	v_and_b32_e32 v179, v200, v223
	v_and_b32_e32 v180, v201, v239
	v_bcnt_u32_b32 v178, v179, 0
	v_bcnt_u32_b32 v178, v180, v178
	s_nop 1
	v_add_u32_dpp v178, v178, v178 quad_perm:[1,0,3,2] row_mask:0xf bank_mask:0xf
	s_nop 1
	v_add_u32_dpp v178, v178, v178 quad_perm:[2,3,0,1] row_mask:0xf bank_mask:0xf
	s_nop 1
	v_add_u32_dpp v178, v178, v178 row_half_mirror row_mask:0xf bank_mask:0xf
	s_nop 1
	v_add_u32_dpp v178, v178, v178 row_mirror row_mask:0xf bank_mask:0xf
	s_nop 1
	v_readlane_b32 s22, v178, 0
	v_readlane_b32 s23, v178, 16
	v_readlane_b32 s24, v178, 32
	v_readlane_b32 s25, v178, 48
	s_add_i32 s22, s22, s23
	s_add_i32 s24, s24, s25
	s_add_i32 s22, s22, s24
	s_cmp_ge_u32 s22, s20
	s_cbranch_scc0 .Ltk_less_15
	v_mov_b32_e32 v200, v179
	v_mov_b32_e32 v201, v180
	s_or_b32 s21, s21, 0x8000
	s_branch .Ltk_next_15
.Ltk_less_15:
	s_sub_u32 s20, s20, s22
	v_xor_b32_e32 v200, v200, v179
	v_xor_b32_e32 v201, v201, v180
.Ltk_next_15:
	v_and_b32_e32 v179, v200, v222
	v_and_b32_e32 v180, v201, v238
	v_bcnt_u32_b32 v178, v179, 0
	v_bcnt_u32_b32 v178, v180, v178
	s_nop 1
	v_add_u32_dpp v178, v178, v178 quad_perm:[1,0,3,2] row_mask:0xf bank_mask:0xf
	s_nop 1
	v_add_u32_dpp v178, v178, v178 quad_perm:[2,3,0,1] row_mask:0xf bank_mask:0xf
	s_nop 1
	v_add_u32_dpp v178, v178, v178 row_half_mirror row_mask:0xf bank_mask:0xf
	s_nop 1
	v_add_u32_dpp v178, v178, v178 row_mirror row_mask:0xf bank_mask:0xf
	s_nop 1
	v_readlane_b32 s22, v178, 0
	v_readlane_b32 s23, v178, 16
	v_readlane_b32 s24, v178, 32
	v_readlane_b32 s25, v178, 48
	s_add_i32 s22, s22, s23
	s_add_i32 s24, s24, s25
	s_add_i32 s22, s22, s24
	s_cmp_ge_u32 s22, s20
	s_cbranch_scc0 .Ltk_less_14
	v_mov_b32_e32 v200, v179
	v_mov_b32_e32 v201, v180
	s_or_b32 s21, s21, 0x4000
	s_branch .Ltk_next_14

; __device__ __forceinline__ void attn_phase(const int TID, const int BID, PP p, LAS unsigned char* lds) {
;     ...
;                 const unsigned cand = Tt | (1u << bit);
;                 int c = 0;
; #pragma unroll
;                 for (int ib = 0; ib < 16; ++ib)
;                     if (ib < nib) {
; #pragma unroll
;                         for (int e = 0; e < 4; ++e) c += (key[4 * ib + e] >= cand) ? 1 : 0;
;                     }
;                 int cnt = 0;
; #pragma unroll
;                 for (int bp = 0; bp < 7; ++bp) cnt += __popcll(__ballot((c >> bp) & 1)) << bp;
;                 if (cnt >= 256) { Tt = cand; if (cnt == 256) break; }
;             }
.Ltk_next_14:
	v_and_b32_e32 v179, v200, v221
	v_and_b32_e32 v180, v201, v237
	v_bcnt_u32_b32 v178, v179, 0
	v_bcnt_u32_b32 v178, v180, v178
	s_nop 1
	v_add_u32_dpp v178, v178, v178 quad_perm:[1,0,3,2] row_mask:0xf bank_mask:0xf
	s_nop 1
	v_add_u32_dpp v178, v178, v178 quad_perm:[2,3,0,1] row_mask:0xf bank_mask:0xf
	s_nop 1
	v_add_u32_dpp v178, v178, v178 row_half_mirror row_mask:0xf bank_mask:0xf
	s_nop 1
	v_add_u32_dpp v178, v178, v178 row_mirror row_mask:0xf bank_mask:0xf
	s_nop 1
	v_readlane_b32 s22, v178, 0
	v_readlane_b32 s23, v178, 16
	v_readlane_b32 s24, v178, 32
	v_readlane_b32 s25, v178, 48
	s_add_i32 s22, s22, s23
	s_add_i32 s24, s24, s25
	s_add_i32 s22, s22, s24
	s_cmp_ge_u32 s22, s20
	s_cbranch_scc0 .Ltk_less_13
	v_mov_b32_e32 v200, v179
	v_mov_b32_e32 v201, v180
	s_or_b32 s21, s21, 0x2000
	s_branch .Ltk_next_13

; __device__ __forceinline__ void attn_phase(const int TID, const int BID, PP p, LAS unsigned char* lds) {
;     ...
;                 const unsigned cand = Tt | (1u << bit);
;                 int c = 0;
; #pragma unroll
;                 for (int ib = 0; ib < 16; ++ib)
;                     if (ib < nib) {
; #pragma unroll
;                         for (int e = 0; e < 4; ++e) c += (key[4 * ib + e] >= cand) ? 1 : 0;
;                     }
;                 int cnt = 0;
; #pragma unroll
;                 for (int bp = 0; bp < 7; ++bp) cnt += __popcll(__ballot((c >> bp) & 1)) << bp;
;                 if (cnt >= 256) { Tt = cand; if (cnt == 256) break; }
;             }
.Ltk_next_13:
	v_and_b32_e32 v179, v200, v220
	v_and_b32_e32 v180, v201, v236
	v_bcnt_u32_b32 v178, v179, 0
	v_bcnt_u32_b32 v178, v180, v178
	s_nop 1
	v_add_u32_dpp v178, v178, v178 quad_perm:[1,0,3,2] row_mask:0xf bank_mask:0xf
	s_nop 1
	v_add_u32_dpp v178, v178, v178 quad_perm:[2,3,0,1] row_mask:0xf bank_mask:0xf
	s_nop 1
	v_add_u32_dpp v178, v178, v178 row_half_mirror row_mask:0xf bank_mask:0xf
	s_nop 1
	v_add_u32_dpp v178, v178, v178 row_mirror row_mask:0xf bank_mask:0xf
	s_nop 1
	v_readlane_b32 s22, v178, 0
	v_readlane_b32 s23, v178, 16
	v_readlane_b32 s24, v178, 32
	v_readlane_b32 s25, v178, 48
	s_add_i32 s22, s22, s23
	s_add_i32 s24, s24, s25
	s_add_i32 s22, s22, s24
	s_cmp_ge_u32 s22, s20
	s_cbranch_scc0 .Ltk_less_12
	v_mov_b32_e32 v200, v179
	v_mov_b32_e32 v201, v180
	s_or_b32 s21, s21, 0x1000
	s_branch .Ltk_next_12

; __device__ __forceinline__ void attn_phase(const int TID, const int BID, PP p, LAS unsigned char* lds) {
;     ...
;                 const unsigned cand = Tt | (1u << bit);
;                 int c = 0;
; #pragma unroll
;                 for (int ib = 0; ib < 16; ++ib)
;                     if (ib < nib) {
; #pragma unroll
;                         for (int e = 0; e < 4; ++e) c += (key[4 * ib + e] >= cand) ? 1 : 0;
;                     }
;                 int cnt = 0;
; #pragma unroll
;                 for (int bp = 0; bp < 7; ++bp) cnt += __popcll(__ballot((c >> bp) & 1)) << bp;
;                 if (cnt >= 256) { Tt = cand; if (cnt == 256) break; }
;             }
.Ltk_next_12:
	v_and_b32_e32 v179, v200, v219
	v_and_b32_e32 v180, v201, v235
	v_bcnt_u32_b32 v178, v179, 0
	v_bcnt_u32_b32 v178, v180, v178
	s_nop 1
	v_add_u32_dpp v178, v178, v178 quad_perm:[1,0,3,2] row_mask:0xf bank_mask:0xf
	s_nop 1
	v_add_u32_dpp v178, v178, v178 quad_perm:[2,3,0,1] row_mask:0xf bank_mask:0xf
	s_nop 1
	v_add_u32_dpp v178, v178, v178 row_half_mirror row_mask:0xf bank_mask:0xf
	s_nop 1
	v_add_u32_dpp v178, v178, v178 row_mirror row_mask:0xf bank_mask:0xf
	s_nop 1
	v_readlane_b32 s22, v178, 0
	v_readlane_b32 s23, v178, 16
	v_readlane_b32 s24, v178, 32
	v_readlane_b32 s25, v178, 48
	s_add_i32 s22, s22, s23
	s_add_i32 s24, s24, s25
	s_add_i32 s22, s22, s24
	s_cmp_ge_u32 s22, s20
	s_cbranch_scc0 .Ltk_less_11
	v_mov_b32_e32 v200, v179
	v_mov_b32_e32 v201, v180
	s_or_b32 s21, s21, 0x800
	s_branch .Ltk_next_11

; __device__ __forceinline__ void attn_phase(const int TID, const int BID, PP p, LAS unsigned char* lds) {
;     ...
;                 const unsigned cand = Tt | (1u << bit);
;                 int c = 0;
; #pragma unroll
;                 for (int ib = 0; ib < 16; ++ib)
;                     if (ib < nib) {
; #pragma unroll
;                         for (int e = 0; e < 4; ++e) c += (key[4 * ib + e] >= cand) ? 1 : 0;
;                     }
;                 int cnt = 0;
; #pragma unroll
;                 for (int bp = 0; bp < 7; ++bp) cnt += __popcll(__ballot((c >> bp) & 1)) << bp;
;                 if (cnt >= 256) { Tt = cand; if (cnt == 256) break; }
;             }
.Ltk_next_11:
	v_and_b32_e32 v179, v200, v218
	v_and_b32_e32 v180, v201, v234
	v_bcnt_u32_b32 v178, v179, 0
	v_bcnt_u32_b32 v178, v180, v178
	s_nop 1
	v_add_u32_dpp v178, v178, v178 quad_perm:[1,0,3,2] row_mask:0xf bank_mask:0xf
	s_nop 1
	v_add_u32_dpp v178, v178, v178 quad_perm:[2,3,0,1] row_mask:0xf bank_mask:0xf
	s_nop 1
	v_add_u32_dpp v178, v178, v178 row_half_mirror row_mask:0xf bank_mask:0xf
	s_nop 1
	v_add_u32_dpp v178, v178, v178 row_mirror row_mask:0xf bank_mask:0xf
	s_nop 1
	v_readlane_b32 s22, v178, 0
	v_readlane_b32 s23, v178, 16
	v_readlane_b32 s24, v178, 32
	v_readlane_b32 s25, v178, 48
	s_add_i32 s22, s22, s23
	s_add_i32 s24, s24, s25
	s_add_i32 s22, s22, s24
	s_cmp_ge_u32 s22, s20
	s_cbranch_scc0 .Ltk_less_10
	v_mov_b32_e32 v200, v179
	v_mov_b32_e32 v201, v180
	s_or_b32 s21, s21, 0x400
	s_branch .Ltk_next_10

; __device__ __forceinline__ void attn_phase(const int TID, const int BID, PP p, LAS unsigned char* lds) {
;     ...
;                 const unsigned cand = Tt | (1u << bit);
;                 int c = 0;
; #pragma unroll
;                 for (int ib = 0; ib < 16; ++ib)
;                     if (ib < nib) {
; #pragma unroll
;                         for (int e = 0; e < 4; ++e) c += (key[4 * ib + e] >= cand) ? 1 : 0;
;                     }
;                 int cnt = 0;
; #pragma unroll
;                 for (int bp = 0; bp < 7; ++bp) cnt += __popcll(__ballot((c >> bp) & 1)) << bp;
;                 if (cnt >= 256) { Tt = cand; if (cnt == 256) break; }
;             }
.Ltk_next_10:
	v_and_b32_e32 v179, v200, v217
	v_and_b32_e32 v180, v201, v233
	v_bcnt_u32_b32 v178, v179, 0
	v_bcnt_u32_b32 v178, v180, v178
	s_nop 1
	v_add_u32_dpp v178, v178, v178 quad_perm:[1,0,3,2] row_mask:0xf bank_mask:0xf
	s_nop 1
	v_add_u32_dpp v178, v178, v178 quad_perm:[2,3,0,1] row_mask:0xf bank_mask:0xf
	s_nop 1
	v_add_u32_dpp v178, v178, v178 row_half_mirror row_mask:0xf bank_mask:0xf
	s_nop 1
	v_add_u32_dpp v178, v178, v178 row_mirror row_mask:0xf bank_mask:0xf
	s_nop 1
	v_readlane_b32 s22, v178, 0
	v_readlane_b32 s23, v178, 16
	v_readlane_b32 s24, v178, 32
	v_readlane_b32 s25, v178, 48
	s_add_i32 s22, s22, s23
	s_add_i32 s24, s24, s25
	s_add_i32 s22, s22, s24
	s_cmp_ge_u32 s22, s20
	s_cbranch_scc0 .Ltk_less_9
	v_mov_b32_e32 v200, v179
	v_mov_b32_e32 v201, v180
	s_or_b32 s21, s21, 0x200
	s_branch .Ltk_next_9

; __device__ __forceinline__ void attn_phase(const int TID, const int BID, PP p, LAS unsigned char* lds) {
;     ...
;                 const unsigned cand = Tt | (1u << bit);
;                 int c = 0;
; #pragma unroll
;                 for (int ib = 0; ib < 16; ++ib)
;                     if (ib < nib) {
; #pragma unroll
;                         for (int e = 0; e < 4; ++e) c += (key[4 * ib + e] >= cand) ? 1 : 0;
;                     }
;                 int cnt = 0;
; #pragma unroll
;                 for (int bp = 0; bp < 7; ++bp) cnt += __popcll(__ballot((c >> bp) & 1)) << bp;
;                 if (cnt >= 256) { Tt = cand; if (cnt == 256) break; }
;             }
.Ltk_next_9:
	v_and_b32_e32 v179, v200, v216
	v_and_b32_e32 v180, v201, v232
	v_bcnt_u32_b32 v178, v179, 0
	v_bcnt_u32_b32 v178, v180, v178
	s_nop 1
	v_add_u32_dpp v178, v178, v178 quad_perm:[1,0,3,2] row_mask:0xf bank_mask:0xf
	s_nop 1
	v_add_u32_dpp v178, v178, v178 quad_perm:[2,3,0,1] row_mask:0xf bank_mask:0xf
	s_nop 1
	v_add_u32_dpp v178, v178, v178 row_half_mirror row_mask:0xf bank_mask:0xf
	s_nop 1
	v_add_u32_dpp v178, v178, v178 row_mirror row_mask:0xf bank_mask:0xf
	s_nop 1
	v_readlane_b32 s22, v178, 0
	v_readlane_b32 s23, v178, 16
	v_readlane_b32 s24, v178, 32
	v_readlane_b32 s25, v178, 48
	s_add_i32 s22, s22, s23
	s_add_i32 s24, s24, s25
	s_add_i32 s22, s22, s24
	s_cmp_ge_u32 s22, s20
	s_cbranch_scc0 .Ltk_less_8
	v_mov_b32_e32 v200, v179
	v_mov_b32_e32 v201, v180
	s_or_b32 s21, s21, 0x100
	s_branch .Ltk_next_8

; __device__ __forceinline__ void attn_phase(const int TID, const int BID, PP p, LAS unsigned char* lds) {
;     ...
;                 const unsigned cand = Tt | (1u << bit);
;                 int c = 0;
; #pragma unroll
;                 for (int ib = 0; ib < 16; ++ib)
;                     if (ib < nib) {
; #pragma unroll
;                         for (int e = 0; e < 4; ++e) c += (key[4 * ib + e] >= cand) ? 1 : 0;
;                     }
;                 int cnt = 0;
; #pragma unroll
;                 for (int bp = 0; bp < 7; ++bp) cnt += __popcll(__ballot((c >> bp) & 1)) << bp;
;                 if (cnt >= 256) { Tt = cand; if (cnt == 256) break; }
;             }
.Ltk_next_8:
	v_and_b32_e32 v179, v200, v215
	v_and_b32_e32 v180, v201, v231
	v_bcnt_u32_b32 v178, v179, 0
	v_bcnt_u32_b32 v178, v180, v178
	s_nop 1
	v_add_u32_dpp v178, v178, v178 quad_perm:[1,0,3,2] row_mask:0xf bank_mask:0xf
	s_nop 1
	v_add_u32_dpp v178, v178, v178 quad_perm:[2,3,0,1] row_mask:0xf bank_mask:0xf
	s_nop 1
	v_add_u32_dpp v178, v178, v178 row_half_mirror row_mask:0xf bank_mask:0xf
	s_nop 1
	v_add_u32_dpp v178, v178, v178 row_mirror row_mask:0xf bank_mask:0xf
	s_nop 1
	v_readlane_b32 s22, v178, 0
	v_readlane_b32 s23, v178, 16
	v_readlane_b32 s24, v178, 32
	v_readlane_b32 s25, v178, 48
	s_add_i32 s22, s22, s23
	s_add_i32 s24, s24, s25
	s_add_i32 s22, s22, s24
	s_cmp_ge_u32 s22, s20
	s_cbranch_scc0 .Ltk_less_7
	v_mov_b32_e32 v200, v179
	v_mov_b32_e32 v201, v180
	s_or_b32 s21, s21, 0x80
	s_branch .Ltk_next_7

; __device__ __forceinline__ void attn_phase(const int TID, const int BID, PP p, LAS unsigned char* lds) {
;     ...
;                 const unsigned cand = Tt | (1u << bit);
;                 int c = 0;
; #pragma unroll
;                 for (int ib = 0; ib < 16; ++ib)
;                     if (ib < nib) {
; #pragma unroll
;                         for (int e = 0; e < 4; ++e) c += (key[4 * ib + e] >= cand) ? 1 : 0;
;                     }
;                 int cnt = 0;
; #pragma unroll
;                 for (int bp = 0; bp < 7; ++bp) cnt += __popcll(__ballot((c >> bp) & 1)) << bp;
;                 if (cnt >= 256) { Tt = cand; if (cnt == 256) break; }
;             }
.Ltk_next_7:
	v_and_b32_e32 v179, v200, v214
	v_and_b32_e32 v180, v201, v230
	v_bcnt_u32_b32 v178, v179, 0
	v_bcnt_u32_b32 v178, v180, v178
	s_nop 1
	v_add_u32_dpp v178, v178, v178 quad_perm:[1,0,3,2] row_mask:0xf bank_mask:0xf
	s_nop 1
	v_add_u32_dpp v178, v178, v178 quad_perm:[2,3,0,1] row_mask:0xf bank_mask:0xf
	s_nop 1
	v_add_u32_dpp v178, v178, v178 row_half_mirror row_mask:0xf bank_mask:0xf
	s_nop 1
	v_add_u32_dpp v178, v178, v178 row_mirror row_mask:0xf bank_mask:0xf
	s_nop 1
	v_readlane_b32 s22, v178, 0
	v_readlane_b32 s23, v178, 16
	v_readlane_b32 s24, v178, 32
	v_readlane_b32 s25, v178, 48
	s_add_i32 s22, s22, s23
	s_add_i32 s24, s24, s25
	s_add_i32 s22, s22, s24
	s_cmp_ge_u32 s22, s20
	s_cbranch_scc0 .Ltk_less_6
	v_mov_b32_e32 v200, v179
	v_mov_b32_e32 v201, v180
	s_or_b32 s21, s21, 0x40
	s_branch .Ltk_next_6

; __device__ __forceinline__ void attn_phase(const int TID, const int BID, PP p, LAS unsigned char* lds) {
;     ...
;                 const unsigned cand = Tt | (1u << bit);
;                 int c = 0;
; #pragma unroll
;                 for (int ib = 0; ib < 16; ++ib)
;                     if (ib < nib) {
; #pragma unroll
;                         for (int e = 0; e < 4; ++e) c += (key[4 * ib + e] >= cand) ? 1 : 0;
;                     }
;                 int cnt = 0;
; #pragma unroll
;                 for (int bp = 0; bp < 7; ++bp) cnt += __popcll(__ballot((c >> bp) & 1)) << bp;
;                 if (cnt >= 256) { Tt = cand; if (cnt == 256) break; }
;             }
.Ltk_next_6:
	v_and_b32_e32 v179, v200, v213
	v_and_b32_e32 v180, v201, v229
	v_bcnt_u32_b32 v178, v179, 0
	v_bcnt_u32_b32 v178, v180, v178
	s_nop 1
	v_add_u32_dpp v178, v178, v178 quad_perm:[1,0,3,2] row_mask:0xf bank_mask:0xf
	s_nop 1
	v_add_u32_dpp v178, v178, v178 quad_perm:[2,3,0,1] row_mask:0xf bank_mask:0xf
	s_nop 1
	v_add_u32_dpp v178, v178, v178 row_half_mirror row_mask:0xf bank_mask:0xf
	s_nop 1
	v_add_u32_dpp v178, v178, v178 row_mirror row_mask:0xf bank_mask:0xf
	s_nop 1
	v_readlane_b32 s22, v178, 0
	v_readlane_b32 s23, v178, 16
	v_readlane_b32 s24, v178, 32
	v_readlane_b32 s25, v178, 48
	s_add_i32 s22, s22, s23
	s_add_i32 s24, s24, s25
	s_add_i32 s22, s22, s24
	s_cmp_ge_u32 s22, s20
	s_cbranch_scc0 .Ltk_less_5
	v_mov_b32_e32 v200, v179
	v_mov_b32_e32 v201, v180
	s_or_b32 s21, s21, 0x20
	s_branch .Ltk_next_5

; __device__ __forceinline__ void attn_phase(const int TID, const int BID, PP p, LAS unsigned char* lds) {
;     ...
;                 const unsigned cand = Tt | (1u << bit);
;                 int c = 0;
; #pragma unroll
;                 for (int ib = 0; ib < 16; ++ib)
;                     if (ib < nib) {
; #pragma unroll
;                         for (int e = 0; e < 4; ++e) c += (key[4 * ib + e] >= cand) ? 1 : 0;
;                     }
;                 int cnt = 0;
; #pragma unroll
;                 for (int bp = 0; bp < 7; ++bp) cnt += __popcll(__ballot((c >> bp) & 1)) << bp;
;                 if (cnt >= 256) { Tt = cand; if (cnt == 256) break; }
;             }
.Ltk_next_5:
	v_and_b32_e32 v179, v200, v212
	v_and_b32_e32 v180, v201, v228
	v_bcnt_u32_b32 v178, v179, 0
	v_bcnt_u32_b32 v178, v180, v178
	s_nop 1
	v_add_u32_dpp v178, v178, v178 quad_perm:[1,0,3,2] row_mask:0xf bank_mask:0xf
	s_nop 1
	v_add_u32_dpp v178, v178, v178 quad_perm:[2,3,0,1] row_mask:0xf bank_mask:0xf
	s_nop 1
	v_add_u32_dpp v178, v178, v178 row_half_mirror row_mask:0xf bank_mask:0xf
	s_nop 1
	v_add_u32_dpp v178, v178, v178 row_mirror row_mask:0xf bank_mask:0xf
	s_nop 1
	v_readlane_b32 s22, v178, 0
	v_readlane_b32 s23, v178, 16
	v_readlane_b32 s24, v178, 32
	v_readlane_b32 s25, v178, 48
	s_add_i32 s22, s22, s23
	s_add_i32 s24, s24, s25
	s_add_i32 s22, s22, s24
	s_cmp_ge_u32 s22, s20
	s_cbranch_scc0 .Ltk_less_4
	v_mov_b32_e32 v200, v179
	v_mov_b32_e32 v201, v180
	s_or_b32 s21, s21, 0x10
	s_branch .Ltk_next_4

; __device__ __forceinline__ void attn_phase(const int TID, const int BID, PP p, LAS unsigned char* lds) {
;     ...
;                 const unsigned cand = Tt | (1u << bit);
;                 int c = 0;
; #pragma unroll
;                 for (int ib = 0; ib < 16; ++ib)
;                     if (ib < nib) {
; #pragma unroll
;                         for (int e = 0; e < 4; ++e) c += (key[4 * ib + e] >= cand) ? 1 : 0;
;                     }
;                 int cnt = 0;
; #pragma unroll
;                 for (int bp = 0; bp < 7; ++bp) cnt += __popcll(__ballot((c >> bp) & 1)) << bp;
;                 if (cnt >= 256) { Tt = cand; if (cnt == 256) break; }
;             }
.Ltk_next_4:
	v_and_b32_e32 v179, v200, v211
	v_and_b32_e32 v180, v201, v227
	v_bcnt_u32_b32 v178, v179, 0
	v_bcnt_u32_b32 v178, v180, v178
	s_nop 1
	v_add_u32_dpp v178, v178, v178 quad_perm:[1,0,3,2] row_mask:0xf bank_mask:0xf
	s_nop 1
	v_add_u32_dpp v178, v178, v178 quad_perm:[2,3,0,1] row_mask:0xf bank_mask:0xf
	s_nop 1
	v_add_u32_dpp v178, v178, v178 row_half_mirror row_mask:0xf bank_mask:0xf
	s_nop 1
	v_add_u32_dpp v178, v178, v178 row_mirror row_mask:0xf bank_mask:0xf
	s_nop 1
	v_readlane_b32 s22, v178, 0
	v_readlane_b32 s23, v178, 16
	v_readlane_b32 s24, v178, 32
	v_readlane_b32 s25, v178, 48
	s_add_i32 s22, s22, s23
	s_add_i32 s24, s24, s25
	s_add_i32 s22, s22, s24
	s_cmp_ge_u32 s22, s20
	s_cbranch_scc0 .Ltk_less_3
	v_mov_b32_e32 v200, v179
	v_mov_b32_e32 v201, v180
	s_or_b32 s21, s21, 0x8
	s_branch .Ltk_next_3

; __device__ __forceinline__ void attn_phase(const int TID, const int BID, PP p, LAS unsigned char* lds) {
;     ...
;                 const unsigned cand = Tt | (1u << bit);
;                 int c = 0;
; #pragma unroll
;                 for (int ib = 0; ib < 16; ++ib)
;                     if (ib < nib) {
; #pragma unroll
;                         for (int e = 0; e < 4; ++e) c += (key[4 * ib + e] >= cand) ? 1 : 0;
;                     }
;                 int cnt = 0;
; #pragma unroll
;                 for (int bp = 0; bp < 7; ++bp) cnt += __popcll(__ballot((c >> bp) & 1)) << bp;
;                 if (cnt >= 256) { Tt = cand; if (cnt == 256) break; }
;             }
.Ltk_next_3:
	v_and_b32_e32 v179, v200, v210
	v_and_b32_e32 v180, v201, v226
	v_bcnt_u32_b32 v178, v179, 0
	v_bcnt_u32_b32 v178, v180, v178
	s_nop 1
	v_add_u32_dpp v178, v178, v178 quad_perm:[1,0,3,2] row_mask:0xf bank_mask:0xf
	s_nop 1
	v_add_u32_dpp v178, v178, v178 quad_perm:[2,3,0,1] row_mask:0xf bank_mask:0xf
	s_nop 1
	v_add_u32_dpp v178, v178, v178 row_half_mirror row_mask:0xf bank_mask:0xf
	s_nop 1
	v_add_u32_dpp v178, v178, v178 row_mirror row_mask:0xf bank_mask:0xf
	s_nop 1
	v_readlane_b32 s22, v178, 0
	v_readlane_b32 s23, v178, 16
	v_readlane_b32 s24, v178, 32
	v_readlane_b32 s25, v178, 48
	s_add_i32 s22, s22, s23
	s_add_i32 s24, s24, s25
	s_add_i32 s22, s22, s24
	s_cmp_ge_u32 s22, s20
	s_cbranch_scc0 .Ltk_less_2
	v_mov_b32_e32 v200, v179
	v_mov_b32_e32 v201, v180
	s_or_b32 s21, s21, 0x4
	s_branch .Ltk_next_2

; __device__ __forceinline__ void attn_phase(const int TID, const int BID, PP p, LAS unsigned char* lds) {
;     ...
;                 const unsigned cand = Tt | (1u << bit);
;                 int c = 0;
; #pragma unroll
;                 for (int ib = 0; ib < 16; ++ib)
;                     if (ib < nib) {
; #pragma unroll
;                         for (int e = 0; e < 4; ++e) c += (key[4 * ib + e] >= cand) ? 1 : 0;
;                     }
;                 int cnt = 0;
; #pragma unroll
;                 for (int bp = 0; bp < 7; ++bp) cnt += __popcll(__ballot((c >> bp) & 1)) << bp;
;                 if (cnt >= 256) { Tt = cand; if (cnt == 256) break; }
;             }
.Ltk_next_2:
	v_and_b32_e32 v179, v200, v209
	v_and_b32_e32 v180, v201, v225
	v_bcnt_u32_b32 v178, v179, 0
	v_bcnt_u32_b32 v178, v180, v178
	s_nop 1
	v_add_u32_dpp v178, v178, v178 quad_perm:[1,0,3,2] row_mask:0xf bank_mask:0xf
	s_nop 1
	v_add_u32_dpp v178, v178, v178 quad_perm:[2,3,0,1] row_mask:0xf bank_mask:0xf
	s_nop 1
	v_add_u32_dpp v178, v178, v178 row_half_mirror row_mask:0xf bank_mask:0xf
	s_nop 1
	v_add_u32_dpp v178, v178, v178 row_mirror row_mask:0xf bank_mask:0xf
	s_nop 1
	v_readlane_b32 s22, v178, 0
	v_readlane_b32 s23, v178, 16
	v_readlane_b32 s24, v178, 32
	v_readlane_b32 s25, v178, 48
	s_add_i32 s22, s22, s23
	s_add_i32 s24, s24, s25
	s_add_i32 s22, s22, s24
	s_cmp_ge_u32 s22, s20
	s_cbranch_scc0 .Ltk_less_1
	v_mov_b32_e32 v200, v179
	v_mov_b32_e32 v201, v180
	s_or_b32 s21, s21, 0x2
	s_branch .Ltk_next_1

; __device__ __forceinline__ void attn_phase(const int TID, const int BID, PP p, LAS unsigned char* lds) {
;     ...
;                 const unsigned cand = Tt | (1u << bit);
;                 int c = 0;
; #pragma unroll
;                 for (int ib = 0; ib < 16; ++ib)
;                     if (ib < nib) {
; #pragma unroll
;                         for (int e = 0; e < 4; ++e) c += (key[4 * ib + e] >= cand) ? 1 : 0;
;                     }
;                 int cnt = 0;
; #pragma unroll
;                 for (int bp = 0; bp < 7; ++bp) cnt += __popcll(__ballot((c >> bp) & 1)) << bp;
;                 if (cnt >= 256) { Tt = cand; if (cnt == 256) break; }
;             }
.Ltk_next_1:
	v_and_b32_e32 v179, v200, v208
	v_and_b32_e32 v180, v201, v224
	v_bcnt_u32_b32 v178, v179, 0
	v_bcnt_u32_b32 v178, v180, v178
	s_nop 1
	v_add_u32_dpp v178, v178, v178 quad_perm:[1,0,3,2] row_mask:0xf bank_mask:0xf
	s_nop 1
	v_add_u32_dpp v178, v178, v178 quad_perm:[2,3,0,1] row_mask:0xf bank_mask:0xf
	s_nop 1
	v_add_u32_dpp v178, v178, v178 row_half_mirror row_mask:0xf bank_mask:0xf
	s_nop 1
	v_add_u32_dpp v178, v178, v178 row_mirror row_mask:0xf bank_mask:0xf
	s_nop 1
	v_readlane_b32 s22, v178, 0
	v_readlane_b32 s23, v178, 16
	v_readlane_b32 s24, v178, 32
	v_readlane_b32 s25, v178, 48
	s_add_i32 s22, s22, s23
	s_add_i32 s24, s24, s25
	s_add_i32 s22, s22, s24
	s_cmp_ge_u32 s22, s20
	s_cbranch_scc0 .Ltk_less_0
	v_mov_b32_e32 v200, v179
	v_mov_b32_e32 v201, v180
	s_or_b32 s21, s21, 0x1
	s_branch .Ltk_next_0

; __device__ __forceinline__ void attn_phase(const int TID, const int BID, PP p, LAS unsigned char* lds) {
;     ...
;             }
;             int cnt_gt = 0;
; #pragma unroll
;             for (int ib = 0; ib < 16; ++ib)
;                 if (ib < nib) {
; #pragma unroll
;                     for (int e = 0; e < 4; ++e) cnt_gt += __popcll(__ballot(key[4 * ib + e] > Tt));
;                 }
;             const int need = 256 - cnt_gt;
;             int base = 0, tbase = 0;
; #pragma unroll
;             for (int j = 0; j < 64; ++j) if ((j >> 2) < nib) {
.Ltk_next_0:
	s_mov_b32 s1, 0x8000
	s_bitcmp1_b32 s21, 15
	s_cselect_b32 s0, s1, 0xffff
	s_xor_b32 s0, s21, s0
	v_mov_b32_e32 v5, s0
	v_cvt_f32_f16_e32 v5, v5
	v_ashrrev_i32_e32 v198, 31, v5
	v_or_b32_e32 v198, 0x80000000, v198
	v_xor_b32_e32 v5, v5, v198
	s_not_b64 s[38:39], s[40:41]
	s_not_b64 s[36:37], s[42:43]
	s_not_b64 s[34:35], s[44:45]
	s_not_b64 s[30:31], s[46:47]
	s_not_b64 s[28:29], s[48:49]
	s_not_b64 s[26:27], s[50:51]
	s_not_b64 s[24:25], s[52:53]
	s_not_b64 s[22:23], s[54:55]
	s_not_b64 s[20:21], s[56:57]
	s_not_b64 s[18:19], s[58:59]
	s_not_b64 s[16:17], s[60:61]
	s_not_b64 s[14:15], s[62:63]
	s_not_b64 s[12:13], s[88:89]
	s_not_b64 s[10:11], s[80:81]
